# fwd gate segment also stage-wise (gate math in place across the 16 elements, interleaved with the i-gate MFMA chain)
# speedup vs baseline: 1.0053x; 1.0053x over previous
; #define LAS __attribute__((address_space(3)))
; template <int dir>
; __device__ __forceinline__ void lru_pass(LAS unsigned char* lds, const Params& P, int b, int h, int q, bool dry) {
;     ...
;             const int sbase = 32 * wid + 16 * g;
;             { const int sl = 32 * wid + s_i; const int tlA = dir == 0 ? sl : 255 - sl;
;               const LAS unsigned char* ap = XC + tlA * XC_PITCH + 16 * g;
;               const LAS unsigned char* wrp = WB + nl * XC_PITCH + 16 * g; const LAS unsigned char* wip = wrp + 32 * XC_PITCH;
; #pragma unroll
;               for (int ks = 0; ks < 8; ++ks) { const bf16x8 A = *(const LAS bf16x8*)(ap + 32 * ks);
;                   const bf16x8 Br = *(const LAS bf16x8*)(wrp + 32 * ks), Bi = *(const LAS bf16x8*)(wip + 32 * ks);
;                   zr = __builtin_amdgcn_mfma_f32_32x32x16_bf16(A, Br, zr, 0, 0, 0); zi = __builtin_amdgcn_mfma_f32_32x32x16_bf16(A, Bi, zi, 0, 0, 0); } }
;             unsigned xcb[16], pk[16];
; #pragma unroll
;             for (int v = 0; v < 16; ++v) { const int s = sbase + v; const int tl = dir == 0 ? s : 255 - s; xcb[v] = *(const LAS bf16_t*)(XC + tl * XC_PITCH + chl * 2);
;                 if (dir == 0) pk[v] = *(const LAS bf16_t*)(TIN + tl * IO_NP + nl * 2); else pk[v] = *(const LAS unsigned*)(TIN + tl * IO_WP + nl * 4); }
;             float Pp = 1.f, E = 0.f;
; #pragma unroll
;             for (int v = 0; v < 16; ++v) {
;                 const float xcv = __uint_as_float(xcb[v] << 16);
;                 const float r = __builtin_amdgcn_rcpf(1.0f + __builtin_amdgcn_exp2f(zr[v]));
;                 const float ig = __builtin_amdgcn_rcpf(1.0f + __builtin_amdgcn_exp2f(zi[v]));
;                 const float a = __builtin_amdgcn_exp2f(cl * r);
;                 const float sq = __builtin_amdgcn_sqrtf(fmaf(-a, a, 1.0f));
;                 const float u = sq * ig * xcv;
;                 E = fmaf(a, E, u); Pp *= a; zr[v] = E; zi[v] = Pp; }
.Llruf_wres:
	ds_read_b128 v[120:123], v160
	ds_read_b128 v[124:127], v160 offset:32
	ds_read_b128 v[168:171], v160 offset:64
	ds_read_b128 v[172:175], v160 offset:96
	ds_read_b128 v[176:179], v160 offset:128
	ds_read_b128 v[180:183], v160 offset:160
	ds_read_b128 v[184:187], v160 offset:192
	ds_read_b128 v[188:191], v160 offset:224
	ds_read_b128 v[236:239], v161 offset:8704
	ds_read_b128 v[240:243], v161 offset:8736
	ds_read_b128 v[244:247], v161 offset:8768
	ds_read_b128 v[248:251], v161 offset:8800
	s_waitcnt lgkmcnt(11)
	v_mfma_f32_32x32x16_bf16 v[32:47], v[120:123], v[204:207], v[0:15]
	s_waitcnt lgkmcnt(10)
	v_mfma_f32_32x32x16_bf16 v[32:47], v[124:127], v[208:211], v[32:47]
	s_waitcnt lgkmcnt(9)
	v_mfma_f32_32x32x16_bf16 v[32:47], v[168:171], v[212:215], v[32:47]
	s_waitcnt lgkmcnt(8)
	v_mfma_f32_32x32x16_bf16 v[32:47], v[172:175], v[216:219], v[32:47]
	s_waitcnt lgkmcnt(7)
	v_mfma_f32_32x32x16_bf16 v[32:47], v[176:179], v[220:223], v[32:47]
	s_waitcnt lgkmcnt(6)
	v_mfma_f32_32x32x16_bf16 v[32:47], v[180:183], v[224:227], v[32:47]
	s_waitcnt lgkmcnt(5)
	v_mfma_f32_32x32x16_bf16 v[32:47], v[184:187], v[228:231], v[32:47]
	s_waitcnt lgkmcnt(4)
	v_mfma_f32_32x32x16_bf16 v[32:47], v[188:191], v[232:235], v[32:47]
	s_waitcnt lgkmcnt(3)
	v_mfma_f32_32x32x16_bf16 v[48:63], v[120:123], v[236:239], v[16:31]
	ds_read_b128 v[236:239], v161 offset:8832
	s_nop 9
	v_exp_f32_e32 v32, v32
	v_exp_f32_e32 v33, v33
	v_exp_f32_e32 v34, v34
	v_exp_f32_e32 v35, v35
	v_exp_f32_e32 v36, v36
	v_exp_f32_e32 v37, v37
	v_exp_f32_e32 v38, v38
	v_exp_f32_e32 v39, v39
	s_waitcnt lgkmcnt(3)
	v_mfma_f32_32x32x16_bf16 v[48:63], v[124:127], v[240:243], v[48:63]
	ds_read_b128 v[240:243], v161 offset:8864
	v_exp_f32_e32 v40, v40
	v_exp_f32_e32 v41, v41
	v_exp_f32_e32 v42, v42
	v_exp_f32_e32 v43, v43
	v_exp_f32_e32 v44, v44
	v_exp_f32_e32 v45, v45
	v_exp_f32_e32 v46, v46
	v_exp_f32_e32 v47, v47
	s_waitcnt lgkmcnt(3)
	v_mfma_f32_32x32x16_bf16 v[48:63], v[168:171], v[244:247], v[48:63]
	ds_read_b128 v[244:247], v161 offset:8896
	v_fma_f32 v32, v32, v138, v138
	v_fma_f32 v33, v33, v138, v138
	v_fma_f32 v34, v34, v138, v138
	v_fma_f32 v35, v35, v138, v138
	v_fma_f32 v36, v36, v138, v138
	v_fma_f32 v37, v37, v138, v138
	v_fma_f32 v38, v38, v138, v138
	v_fma_f32 v39, v39, v138, v138
	s_waitcnt lgkmcnt(3)
	v_mfma_f32_32x32x16_bf16 v[48:63], v[172:175], v[248:251], v[48:63]
	ds_read_b128 v[248:251], v161 offset:8928
	v_fma_f32 v40, v40, v138, v138
	v_fma_f32 v41, v41, v138, v138
	v_fma_f32 v42, v42, v138, v138
	v_fma_f32 v43, v43, v138, v138
	v_fma_f32 v44, v44, v138, v138
	v_fma_f32 v45, v45, v138, v138
	v_fma_f32 v46, v46, v138, v138
	v_fma_f32 v47, v47, v138, v138
	s_waitcnt lgkmcnt(3)
	v_mfma_f32_32x32x16_bf16 v[48:63], v[176:179], v[236:239], v[48:63]
	v_rcp_f32_e32 v32, v32
	v_rcp_f32_e32 v33, v33
	v_rcp_f32_e32 v34, v34
	v_rcp_f32_e32 v35, v35
	v_rcp_f32_e32 v36, v36
	v_rcp_f32_e32 v37, v37
	v_rcp_f32_e32 v38, v38
	v_rcp_f32_e32 v39, v39
	s_waitcnt lgkmcnt(2)
	v_mfma_f32_32x32x16_bf16 v[48:63], v[180:183], v[240:243], v[48:63]
	v_rcp_f32_e32 v40, v40
	v_rcp_f32_e32 v41, v41
	v_rcp_f32_e32 v42, v42
	v_rcp_f32_e32 v43, v43
	v_rcp_f32_e32 v44, v44
	v_rcp_f32_e32 v45, v45
	v_rcp_f32_e32 v46, v46
	v_rcp_f32_e32 v47, v47
	s_waitcnt lgkmcnt(1)
	v_mfma_f32_32x32x16_bf16 v[48:63], v[184:187], v[244:247], v[48:63]
	v_exp_f32_e32 v32, v32
	v_exp_f32_e32 v33, v33
	v_exp_f32_e32 v34, v34
	v_exp_f32_e32 v35, v35
	v_exp_f32_e32 v36, v36
	v_exp_f32_e32 v37, v37
	v_exp_f32_e32 v38, v38
	v_exp_f32_e32 v39, v39
	s_waitcnt lgkmcnt(0)
	v_mfma_f32_32x32x16_bf16 v[48:63], v[188:191], v[248:251], v[48:63]
	v_exp_f32_e32 v40, v40
	v_exp_f32_e32 v41, v41
	v_exp_f32_e32 v42, v42
	v_exp_f32_e32 v43, v43
	v_exp_f32_e32 v44, v44
	v_exp_f32_e32 v45, v45
	v_exp_f32_e32 v46, v46
	v_exp_f32_e32 v47, v47
	ds_read_u16 v152, v162
	ds_read_u16 v154, v162 offset:272
	ds_read_u16 v155, v162 offset:544
	ds_read_u16 v157, v162 offset:816
	ds_read_u16 v196, v162 offset:1088
	ds_read_u16 v197, v162 offset:1360
	ds_read_u16 v177, v162 offset:1632
	ds_read_u16 v178, v162 offset:1904
	ds_read_u16 v179, v162 offset:2176
	ds_read_u16 v180, v162 offset:2448
	ds_read_u16 v181, v162 offset:2720
	ds_read_u16 v182, v162 offset:2992
	ds_read_u16 v183, v162 offset:3264
	ds_read_u16 v184, v162 offset:3536
	ds_read_u16 v185, v162 offset:3808
	ds_read_u16 v187, v162 offset:4080
	v_exp_f32_e32 v48, v48
	v_exp_f32_e32 v49, v49
	v_exp_f32_e32 v50, v50
	v_exp_f32_e32 v51, v51
	v_exp_f32_e32 v52, v52
	v_exp_f32_e32 v53, v53
	v_exp_f32_e32 v54, v54
	v_exp_f32_e32 v55, v55
	v_exp_f32_e32 v56, v56
	v_exp_f32_e32 v57, v57
	v_exp_f32_e32 v58, v58
	v_exp_f32_e32 v59, v59
	v_exp_f32_e32 v60, v60
	v_exp_f32_e32 v61, v61
	v_exp_f32_e32 v62, v62
	v_exp_f32_e32 v63, v63
	v_add_f32_e32 v48, 1.0, v48
	v_add_f32_e32 v49, 1.0, v49
	v_add_f32_e32 v50, 1.0, v50
	v_add_f32_e32 v51, 1.0, v51
	v_add_f32_e32 v52, 1.0, v52
	v_add_f32_e32 v53, 1.0, v53
	v_add_f32_e32 v54, 1.0, v54
	v_add_f32_e32 v55, 1.0, v55
	v_add_f32_e32 v56, 1.0, v56
	v_add_f32_e32 v57, 1.0, v57
	v_add_f32_e32 v58, 1.0, v58
	v_add_f32_e32 v59, 1.0, v59
	v_add_f32_e32 v60, 1.0, v60
	v_add_f32_e32 v61, 1.0, v61
	v_add_f32_e32 v62, 1.0, v62
	v_add_f32_e32 v63, 1.0, v63
	v_rcp_f32_e32 v48, v48
	v_rcp_f32_e32 v49, v49
	v_rcp_f32_e32 v50, v50
	v_rcp_f32_e32 v51, v51
	v_rcp_f32_e32 v52, v52
	v_rcp_f32_e32 v53, v53
	v_rcp_f32_e32 v54, v54
	v_rcp_f32_e32 v55, v55
	v_rcp_f32_e32 v56, v56
	v_rcp_f32_e32 v57, v57
	v_rcp_f32_e32 v58, v58
	v_rcp_f32_e32 v59, v59
	v_rcp_f32_e32 v60, v60
	v_rcp_f32_e32 v61, v61
	v_rcp_f32_e32 v62, v62
	v_rcp_f32_e32 v63, v63
	s_waitcnt lgkmcnt(0)
; template <int dir>
; __device__ __forceinline__ void lru_pass(LAS unsigned char* lds, const Params& P, int b, int h, int q, bool dry) {
;     ...
;             for (int v = 0; v < 16; ++v) {
;                 const float xcv = __uint_as_float(xcb[v] << 16);
;                 const float r = __builtin_amdgcn_rcpf(1.0f + __builtin_amdgcn_exp2f(zr[v]));
;                 const float ig = __builtin_amdgcn_rcpf(1.0f + __builtin_amdgcn_exp2f(zi[v]));
;                 const float a = __builtin_amdgcn_exp2f(cl * r);
;                 const float sq = __builtin_amdgcn_sqrtf(fmaf(-a, a, 1.0f));
;                 const float u = sq * ig * xcv;
;                 E = fmaf(a, E, u); Pp *= a; zr[v] = E; zi[v] = Pp; }
;             const float Po = __shfl_xor(Pp, 32), Eo = __shfl_xor(E, 32);
;             const float P0 = g ? Po : Pp, E0 = g ? Eo : E, P1 = g ? Pp : Po, E1 = g ? E : Eo;
;             if (g == 0) { AGG[(wid * 2 + 0) * 32 + nl] = P0 * P1; AGG[(wid * 2 + 1) * 32 + nl] = fmaf(P1, E0, E1); }
	v_fma_f32 v120, -v32, v32, 1.0
	v_fma_f32 v121, -v33, v33, 1.0
	v_fma_f32 v122, -v34, v34, 1.0
	v_fma_f32 v123, -v35, v35, 1.0
	v_sqrt_f32_e32 v120, v120
	v_sqrt_f32_e32 v121, v121
	v_sqrt_f32_e32 v122, v122
	v_sqrt_f32_e32 v123, v123
	v_lshlrev_b32_e32 v152, 16, v152
	v_lshlrev_b32_e32 v154, 16, v154
	v_lshlrev_b32_e32 v155, 16, v155
	v_lshlrev_b32_e32 v157, 16, v157
	v_mul_f32_e32 v120, v120, v48
	v_mul_f32_e32 v121, v121, v49
	v_mul_f32_e32 v122, v122, v50
	v_mul_f32_e32 v123, v123, v51
	v_mul_f32_e32 v49, v120, v152
	v_mul_f32_e32 v172, v121, v154
	v_mul_f32_e32 v173, v122, v155
	v_mul_f32_e32 v174, v123, v157
	v_fma_f32 v120, -v36, v36, 1.0
	v_fma_f32 v121, -v37, v37, 1.0
	v_fma_f32 v122, -v38, v38, 1.0
	v_fma_f32 v123, -v39, v39, 1.0
	v_sqrt_f32_e32 v120, v120
	v_sqrt_f32_e32 v121, v121
	v_sqrt_f32_e32 v122, v122
	v_sqrt_f32_e32 v123, v123
	v_lshlrev_b32_e32 v196, 16, v196
	v_lshlrev_b32_e32 v197, 16, v197
	v_lshlrev_b32_e32 v177, 16, v177
	v_lshlrev_b32_e32 v178, 16, v178
	v_mul_f32_e32 v120, v120, v52
	v_mul_f32_e32 v121, v121, v53
	v_mul_f32_e32 v122, v122, v54
	v_mul_f32_e32 v123, v123, v55
	v_mul_f32_e32 v175, v120, v196
	v_mul_f32_e32 v176, v121, v197
	v_mul_f32_e32 v177, v122, v177
	v_mul_f32_e32 v178, v123, v178
	v_fma_f32 v120, -v40, v40, 1.0
	v_fma_f32 v121, -v41, v41, 1.0
	v_fma_f32 v122, -v42, v42, 1.0
	v_fma_f32 v123, -v43, v43, 1.0
	v_sqrt_f32_e32 v120, v120
	v_sqrt_f32_e32 v121, v121
	v_sqrt_f32_e32 v122, v122
	v_sqrt_f32_e32 v123, v123
	v_lshlrev_b32_e32 v179, 16, v179
	v_lshlrev_b32_e32 v180, 16, v180
	v_lshlrev_b32_e32 v181, 16, v181
	v_lshlrev_b32_e32 v182, 16, v182
	v_mul_f32_e32 v120, v120, v56
	v_mul_f32_e32 v121, v121, v57
	v_mul_f32_e32 v122, v122, v58
	v_mul_f32_e32 v123, v123, v59
	v_mul_f32_e32 v179, v120, v179
	v_mul_f32_e32 v180, v121, v180
	v_mul_f32_e32 v181, v122, v181
	v_mul_f32_e32 v182, v123, v182
	v_fma_f32 v120, -v44, v44, 1.0
	v_fma_f32 v121, -v45, v45, 1.0
	v_fma_f32 v122, -v46, v46, 1.0
	v_fma_f32 v123, -v47, v47, 1.0
	v_sqrt_f32_e32 v120, v120
	v_sqrt_f32_e32 v121, v121
	v_sqrt_f32_e32 v122, v122
	v_sqrt_f32_e32 v123, v123
	v_lshlrev_b32_e32 v183, 16, v183
	v_lshlrev_b32_e32 v184, 16, v184
	v_lshlrev_b32_e32 v185, 16, v185
	v_lshlrev_b32_e32 v187, 16, v187
	v_mul_f32_e32 v120, v120, v60
	v_mul_f32_e32 v121, v121, v61
	v_mul_f32_e32 v122, v122, v62
	v_mul_f32_e32 v123, v123, v63
	v_mul_f32_e32 v183, v120, v183
	v_mul_f32_e32 v184, v121, v184
	v_mul_f32_e32 v63, v122, v185
	v_mul_f32_e32 v185, v123, v187
	v_mov_b32_e32 v171, v32
	v_fmac_f32_e32 v49, 0, v32
	v_fmac_f32_e32 v172, v33, v49
	v_mul_f32_e32 v50, v171, v33
	v_fmac_f32_e32 v173, v34, v172
	v_mul_f32_e32 v51, v50, v34
	v_fmac_f32_e32 v174, v35, v173
	v_mul_f32_e32 v52, v51, v35
	v_fmac_f32_e32 v175, v36, v174
	v_mul_f32_e32 v53, v52, v36
	v_fmac_f32_e32 v176, v37, v175
	v_mul_f32_e32 v54, v53, v37
	v_fmac_f32_e32 v177, v38, v176
	v_mul_f32_e32 v55, v54, v38
	v_fmac_f32_e32 v178, v39, v177
	v_mul_f32_e32 v56, v55, v39
	v_fmac_f32_e32 v179, v40, v178
	v_mul_f32_e32 v57, v56, v40
	v_fmac_f32_e32 v180, v41, v179
	v_mul_f32_e32 v58, v57, v41
	v_fmac_f32_e32 v181, v42, v180
	v_mul_f32_e32 v59, v58, v42
	v_fmac_f32_e32 v182, v43, v181
	v_mul_f32_e32 v60, v59, v43
	v_fmac_f32_e32 v183, v44, v182
	v_mul_f32_e32 v61, v60, v44
	v_fmac_f32_e32 v184, v45, v183
	v_mul_f32_e32 v62, v61, v45
	v_fmac_f32_e32 v63, v46, v184
	v_mul_f32_e32 v186, v62, v46
	v_fmac_f32_e32 v185, v47, v63
	v_mul_f32_e32 v187, v186, v47
	v_mov_b32_e32 v188, v187
	v_mov_b32_e32 v252, v187
	v_mov_b32_e32 v189, v185
	v_mov_b32_e32 v253, v185
	s_nop 1
	v_permlane32_swap_b32 v188, v252
	v_permlane32_swap_b32 v189, v253
	s_and_saveexec_b64 s[18:19], vcc
	s_cbranch_execz .LBB0_299
	v_fma_f32 v32, v252, v189, v253
	v_mul_f32_e32 v33, v188, v252
	v_add_u32_e32 v35, s98, v147
	ds_write2_b32 v35, v33, v32 offset1:32
